# hand-written steady-state attention loop: waves 4-7 staggered (LDS store + next-tile loads first), saddr loads with precomputed lane offsets, counted vmcnt
# speedup vs baseline: 1.0247x; 1.0156x over previous
.Lfa_pre:
	s_cmp_gt_i32 s62, 5
	s_cbranch_scc0 .LBB0_709
	v_readfirstlane_b32 s73, v252
	s_nop 3
	s_cmp_gt_i32 s67, 0
	s_cselect_b32 s74, 1, 0
	s_bfe_u32 s73, s73, 0x10008
	s_and_b64 s[68:69], s[26:27], exec
	s_movk_i32 s72, 0x400
	s_cselect_b32 s72, 0x1c00, s72
	s_sub_i32 s75, s30, 64
	v_mul_lo_u32 v205, v193, s72
	s_mul_i32 s75, s75, s72
	s_lshl_b32 s70, s72, 5
	s_lshl_b32 s72, s72, 6
	v_lshl_add_u32 v205, v181, 1, v205
	v_add_u32_e32 v206, s70, v205
	s_and_b64 s[68:69], s[26:27], exec
	s_cbranch_scc0 .Lfa_k1
	s_add_u32 s68, s18, s24
	s_addc_u32 s69, s19, 0
	s_add_u32 s68, s68, 0x1400
	s_addc_u32 s69, s69, 0
	s_add_u32 s68, s68, s75
	s_addc_u32 s69, s69, 0
	s_add_u32 s70, s68, 0x400
	s_addc_u32 s71, s69, 0
	s_branch .Lfa_loop
.Lfa_k1:
	s_add_u32 s68, s63, s75
	s_addc_u32 s69, s64, 0
	s_add_u32 s70, s65, s75
	s_addc_u32 s71, s66, 0
.Lfa_loop:
	s_cmp_eq_u32 s73, 0
	s_cbranch_scc1 .Lfa_e_a
	s_waitcnt vmcnt(2)
	ds_write_b128 v14, v[160:163] offset:37888
	ds_write_b128 v15, v[164:167] offset:55296
	s_waitcnt vmcnt(1)
	ds_write_b128 v202, v[168:171] offset:37888
	s_waitcnt vmcnt(0)
	ds_write_b128 v203, v[172:175] offset:55296
	global_load_dwordx4 v[144:147], v205, s[68:69]
	global_load_dwordx4 v[148:151], v205, s[70:71]
	global_load_dwordx4 v[152:155], v206, s[68:69]
	global_load_dwordx4 v[156:159], v206, s[70:71]
	s_cmp_eq_u32 s74, 0
	s_cbranch_scc1 .Lfa_e_bar
	s_waitcnt lgkmcnt(3)
.Lfa_e_a:
	ds_read_b128 v[212:215], v201 offset:0
	ds_read_b128 v[216:219], v201 offset:8704
	ds_read_b128 v[220:223], v201 offset:32
	ds_read_b128 v[224:227], v201 offset:8736
	ds_read_b128 v[228:231], v201 offset:64
	ds_read_b128 v[232:235], v201 offset:8768
	ds_read_b128 v[236:239], v201 offset:96
	ds_read_b128 v[240:243], v201 offset:8800
	ds_read_b64_tr_b16 v[244:245], v200 offset:17408
	ds_read_b64_tr_b16 v[246:247], v200 offset:19968
	ds_read_b64_tr_b16 v[248:249], v200 offset:17472
	ds_read_b64_tr_b16 v[250:251], v200 offset:20032
	s_waitcnt lgkmcnt(11)
	v_mfma_f32_32x32x16_bf16 v[96:111], v[212:215], v[128:131], v[16:31]
	s_waitcnt lgkmcnt(10)
	v_mfma_f32_32x32x16_bf16 v[112:127], v[216:219], v[128:131], v[16:31]
	s_waitcnt lgkmcnt(9)
	v_mfma_f32_32x32x16_bf16 v[96:111], v[220:223], v[132:135], v[96:111]
	s_waitcnt lgkmcnt(8)
	v_mfma_f32_32x32x16_bf16 v[112:127], v[224:227], v[132:135], v[112:127]
	s_waitcnt lgkmcnt(7)
	v_mfma_f32_32x32x16_bf16 v[96:111], v[228:231], v[136:139], v[96:111]
	s_waitcnt lgkmcnt(6)
	v_mfma_f32_32x32x16_bf16 v[112:127], v[232:235], v[136:139], v[112:127]
	s_waitcnt lgkmcnt(5)
	v_mfma_f32_32x32x16_bf16 v[96:111], v[236:239], v[140:143], v[96:111]
	s_waitcnt lgkmcnt(4)
	v_mfma_f32_32x32x16_bf16 v[112:127], v[240:243], v[140:143], v[112:127]
	ds_read_b64_tr_b16 v[212:213], v200 offset:17536
	ds_read_b64_tr_b16 v[214:215], v200 offset:20096
	ds_read_b64_tr_b16 v[216:217], v200 offset:17600
	ds_read_b64_tr_b16 v[218:219], v200 offset:20160
	ds_read_b64_tr_b16 v[220:221], v200 offset:22528
	ds_read_b64_tr_b16 v[222:223], v200 offset:25088
	ds_read_b64_tr_b16 v[224:225], v200 offset:22592
	ds_read_b64_tr_b16 v[226:227], v200 offset:25152
	ds_read_b64_tr_b16 v[228:229], v200 offset:22656
	ds_read_b64_tr_b16 v[230:231], v200 offset:25216
	s_cmp_lg_u32 s73, 0
	s_cbranch_scc1 .Lfa_e_now1
	global_load_dwordx4 v[144:147], v205, s[68:69]
	global_load_dwordx4 v[148:151], v205, s[70:71]
	global_load_dwordx4 v[152:155], v206, s[68:69]
	global_load_dwordx4 v[156:159], v206, s[70:71]
.Lfa_e_now1:
	s_nop 3
	v_max3_f32 v0, v96, v97, v112
	v_max3_f32 v2, v98, v99, v113
	s_nop 0
	v_max3_f32 v0, v0, v114, v115
	v_max3_f32 v2, v2, v102, v103
	s_nop 0
	v_max3_f32 v0, v0, v100, v101
	v_max3_f32 v2, v2, v118, v119
	s_nop 0
	v_max3_f32 v0, v0, v116, v117
	v_max3_f32 v2, v2, v106, v107
	s_nop 0
	v_max3_f32 v0, v0, v104, v105
	v_max3_f32 v2, v2, v122, v123
	s_nop 0
	v_max3_f32 v0, v0, v120, v121
	v_max3_f32 v2, v2, v110, v111
	s_nop 0
	v_max3_f32 v0, v0, v108, v109
	v_max3_f32 v2, v2, v126, v127
	s_nop 0
	v_max3_f32 v0, v0, v124, v125
	v_max_f32_e32 v2, v2, v2
	v_max_f32_e32 v0, v0, v0
	v_max_f32_e32 v0, v0, v2
	v_mov_b32_e32 v2, v0
	s_nop 1
	v_permlane32_swap_b32_e32 v0, v2
	v_max_f32_e32 v2, v2, v2
	v_max_f32_e32 v0, v0, v0
	v_max_f32_e32 v0, v0, v2
	v_cmp_lt_f32_e32 vcc, s57, v0
	s_cbranch_vccz .Lfa_e_sm
	v_max_f32_e32 v0, v0, v0
	v_max_f32_e32 v2, 0, v0
	v_exp_f32_e64 v0, -v2
	v_add_f32_e32 v182, v182, v2
	v_xor_b32_e32 v16, 0x80000000, v182
	v_mov_b32_e32 v17, v16
	v_mov_b32_e32 v18, v16
	v_mov_b32_e32 v19, v16
	v_mov_b32_e32 v20, v16
	v_mov_b32_e32 v21, v16
	v_mov_b32_e32 v22, v16
	v_mov_b32_e32 v23, v16
	v_mov_b32_e32 v24, v16
	v_mov_b32_e32 v25, v16
	v_mov_b32_e32 v26, v16
	v_mov_b32_e32 v27, v16
	v_mov_b32_e32 v28, v16
	v_mov_b32_e32 v29, v16
	v_mov_b32_e32 v30, v16
	v_mov_b32_e32 v31, v16
	v_sub_f32_e32 v112, v112, v2
	v_sub_f32_e32 v113, v113, v2
	v_sub_f32_e32 v114, v114, v2
	v_sub_f32_e32 v115, v115, v2
	v_sub_f32_e32 v116, v116, v2
	v_sub_f32_e32 v117, v117, v2
	v_sub_f32_e32 v118, v118, v2
	v_sub_f32_e32 v119, v119, v2
	v_sub_f32_e32 v120, v120, v2
	v_sub_f32_e32 v121, v121, v2
	v_sub_f32_e32 v122, v122, v2
	v_sub_f32_e32 v123, v123, v2
	v_sub_f32_e32 v124, v124, v2
	v_sub_f32_e32 v125, v125, v2
	v_sub_f32_e32 v126, v126, v2
	v_sub_f32_e32 v127, v127, v2
	v_sub_f32_e32 v96, v96, v2
	v_sub_f32_e32 v97, v97, v2
	v_sub_f32_e32 v98, v98, v2
	v_sub_f32_e32 v99, v99, v2
	v_sub_f32_e32 v100, v100, v2
	v_sub_f32_e32 v101, v101, v2
	v_sub_f32_e32 v102, v102, v2
	v_sub_f32_e32 v103, v103, v2
	v_sub_f32_e32 v104, v104, v2
	v_sub_f32_e32 v105, v105, v2
	v_sub_f32_e32 v106, v106, v2
	v_sub_f32_e32 v107, v107, v2
	v_sub_f32_e32 v108, v108, v2
	v_sub_f32_e32 v109, v109, v2
	v_sub_f32_e32 v110, v110, v2
	v_sub_f32_e32 v111, v111, v2
	v_mul_f32_e32 v183, v183, v0
	v_pk_mul_f32 v[94:95], v[94:95], v[0:1] op_sel_hi:[1,0]
	v_pk_mul_f32 v[92:93], v[92:93], v[0:1] op_sel_hi:[1,0]
	v_pk_mul_f32 v[90:91], v[90:91], v[0:1] op_sel_hi:[1,0]
	v_pk_mul_f32 v[88:89], v[88:89], v[0:1] op_sel_hi:[1,0]
	v_pk_mul_f32 v[86:87], v[86:87], v[0:1] op_sel_hi:[1,0]
	v_pk_mul_f32 v[84:85], v[84:85], v[0:1] op_sel_hi:[1,0]
	v_pk_mul_f32 v[82:83], v[82:83], v[0:1] op_sel_hi:[1,0]
	v_pk_mul_f32 v[80:81], v[80:81], v[0:1] op_sel_hi:[1,0]
	v_pk_mul_f32 v[78:79], v[78:79], v[0:1] op_sel_hi:[1,0]
	v_pk_mul_f32 v[76:77], v[76:77], v[0:1] op_sel_hi:[1,0]
	v_pk_mul_f32 v[74:75], v[74:75], v[0:1] op_sel_hi:[1,0]
	v_pk_mul_f32 v[72:73], v[72:73], v[0:1] op_sel_hi:[1,0]
	v_pk_mul_f32 v[70:71], v[70:71], v[0:1] op_sel_hi:[1,0]
	v_pk_mul_f32 v[68:69], v[68:69], v[0:1] op_sel_hi:[1,0]
	v_pk_mul_f32 v[66:67], v[66:67], v[0:1] op_sel_hi:[1,0]
	v_pk_mul_f32 v[64:65], v[64:65], v[0:1] op_sel_hi:[1,0]
	v_pk_mul_f32 v[62:63], v[62:63], v[0:1] op_sel_hi:[1,0]
	v_pk_mul_f32 v[60:61], v[60:61], v[0:1] op_sel_hi:[1,0]
	v_pk_mul_f32 v[58:59], v[58:59], v[0:1] op_sel_hi:[1,0]
	v_pk_mul_f32 v[56:57], v[56:57], v[0:1] op_sel_hi:[1,0]
	v_pk_mul_f32 v[54:55], v[54:55], v[0:1] op_sel_hi:[1,0]
	v_pk_mul_f32 v[52:53], v[52:53], v[0:1] op_sel_hi:[1,0]
	v_pk_mul_f32 v[50:51], v[50:51], v[0:1] op_sel_hi:[1,0]
	v_pk_mul_f32 v[48:49], v[48:49], v[0:1] op_sel_hi:[1,0]
	v_pk_mul_f32 v[46:47], v[46:47], v[0:1] op_sel_hi:[1,0]
	v_pk_mul_f32 v[44:45], v[44:45], v[0:1] op_sel_hi:[1,0]
	v_pk_mul_f32 v[42:43], v[42:43], v[0:1] op_sel_hi:[1,0]
	v_pk_mul_f32 v[40:41], v[40:41], v[0:1] op_sel_hi:[1,0]
	v_pk_mul_f32 v[38:39], v[38:39], v[0:1] op_sel_hi:[1,0]
	v_pk_mul_f32 v[36:37], v[36:37], v[0:1] op_sel_hi:[1,0]
	v_pk_mul_f32 v[34:35], v[34:35], v[0:1] op_sel_hi:[1,0]
	v_pk_mul_f32 v[32:33], v[32:33], v[0:1] op_sel_hi:[1,0]
.Lfa_e_sm:
	s_waitcnt lgkmcnt(9)
	ds_read_b64_tr_b16 v[232:233], v200 offset:22720
	ds_read_b64_tr_b16 v[234:235], v200 offset:25280
	ds_read_b64_tr_b16 v[236:237], v200 offset:27648
	ds_read_b64_tr_b16 v[238:239], v200 offset:30208
	ds_read_b64_tr_b16 v[240:241], v200 offset:27712
	ds_read_b64_tr_b16 v[242:243], v200 offset:30272
	v_exp_f32_e32 v176, v96
	v_exp_f32_e32 v177, v112
	v_exp_f32_e32 v0, v97
	v_exp_f32_e32 v2, v113
	v_exp_f32_e32 v204, v114
	v_add_f32_e32 v3, v177, v176
	v_exp_f32_e32 v8, v115
	v_pk_add_f32 v[4:5], v[2:3], v[0:1]
	v_exp_f32_e32 v3, v98
	v_pk_add_f32 v[4:5], v[4:5], v[4:5] op_sel_hi:[0,1]
	v_exp_f32_e32 v4, v99
	v_exp_f32_e32 v112, v117
	v_add_f32_e32 v9, v204, v3
	v_exp_f32_e32 v114, v123
	v_pk_add_f32 v[6:7], v[8:9], v[4:5]
	v_exp_f32_e32 v5, v100
	v_pk_add_f32 v[6:7], v[6:7], v[6:7] op_sel_hi:[0,1]
	v_exp_f32_e32 v9, v116
	v_exp_f32_e32 v6, v101
	v_exp_f32_e32 v100, v119
	v_exp_f32_e32 v116, v125
	v_add_f32_e32 v113, v9, v5
	v_pk_add_f32 v[10:11], v[112:113], v[6:7]
	v_exp_f32_e32 v7, v102
	v_pk_add_f32 v[10:11], v[10:11], v[10:11] op_sel_hi:[0,1]
	v_exp_f32_e32 v113, v118
	v_exp_f32_e32 v10, v103
	v_exp_f32_e32 v102, v121
	v_exp_f32_e32 v118, v127
	v_add_f32_e32 v101, v113, v7
	v_pk_add_f32 v[12:13], v[100:101], v[10:11]
	v_exp_f32_e32 v11, v104
	v_pk_add_f32 v[12:13], v[12:13], v[12:13] op_sel_hi:[0,1]
	v_exp_f32_e32 v101, v120
	v_exp_f32_e32 v12, v105
	v_cvt_pk_bf16_f32 v98, v5, v6
	v_cvt_pk_bf16_f32 v99, v7, v10
	v_add_f32_e32 v103, v101, v11
	v_pk_add_f32 v[96:97], v[102:103], v[12:13]
	v_exp_f32_e32 v13, v106
	v_pk_add_f32 v[104:105], v[96:97], v[96:97] op_sel_hi:[0,1]
	v_exp_f32_e32 v103, v122
	v_exp_f32_e32 v104, v107
	v_cvt_pk_bf16_f32 v6, v177, v2
	v_cvt_pk_bf16_f32 v7, v204, v8
	v_add_f32_e32 v115, v103, v13
	v_pk_add_f32 v[96:97], v[114:115], v[104:105]
	v_exp_f32_e32 v105, v108
	v_pk_add_f32 v[106:107], v[96:97], v[96:97] op_sel_hi:[0,1]
	v_exp_f32_e32 v115, v124
	v_exp_f32_e32 v106, v109
	v_cvt_pk_bf16_f32 v8, v9, v112
	v_cvt_pk_bf16_f32 v9, v113, v100
	v_add_f32_e32 v117, v115, v105
	v_pk_add_f32 v[96:97], v[116:117], v[106:107]
	v_exp_f32_e32 v107, v110
	v_pk_add_f32 v[108:109], v[96:97], v[96:97] op_sel_hi:[0,1]
	v_exp_f32_e32 v110, v126
	v_exp_f32_e32 v108, v111
	v_cvt_pk_bf16_f32 v2, v101, v102
	v_cvt_pk_bf16_f32 v10, v11, v12
	v_add_f32_e32 v119, v110, v107
	v_pk_add_f32 v[96:97], v[118:119], v[108:109]
	v_cvt_pk_bf16_f32 v11, v13, v104
	v_add_f32_e32 v96, v96, v97
	v_cvt_pk_bf16_f32 v97, v3, v4
	v_cvt_pk_bf16_f32 v3, v103, v114
	v_add_f32_e32 v183, v183, v96
	v_cvt_pk_bf16_f32 v96, v176, v0
	v_cvt_pk_bf16_f32 v12, v105, v106
	v_cvt_pk_bf16_f32 v13, v107, v108
	v_cvt_pk_bf16_f32 v4, v115, v116
	v_cvt_pk_bf16_f32 v5, v110, v118
	s_waitcnt lgkmcnt(3)
	ds_read_b64_tr_b16 v[104:105], v200 offset:27776
	ds_read_b64_tr_b16 v[106:107], v200 offset:30336
	ds_read_b64_tr_b16 v[108:109], v200 offset:27840
	ds_read_b64_tr_b16 v[110:111], v200 offset:30400
	ds_read_b64_tr_b16 v[112:113], v200 offset:32768
	ds_read_b64_tr_b16 v[114:115], v200 offset:35328
	ds_read_b64_tr_b16 v[116:117], v200 offset:32832
	ds_read_b64_tr_b16 v[118:119], v200 offset:35392
	ds_read_b64_tr_b16 v[120:121], v200 offset:32896
	ds_read_b64_tr_b16 v[122:123], v200 offset:35456
	ds_read_b64_tr_b16 v[124:125], v200 offset:32960
	ds_read_b64_tr_b16 v[126:127], v200 offset:35520
	v_mfma_f32_32x32x16_bf16 v[80:95], v[244:247], v[96:99], v[80:95]
	v_mfma_f32_32x32x16_bf16 v[64:79], v[248:251], v[96:99], v[64:79]
	v_mfma_f32_32x32x16_bf16 v[48:63], v[212:215], v[96:99], v[48:63]
	v_mfma_f32_32x32x16_bf16 v[32:47], v[216:219], v[96:99], v[32:47]
	v_mfma_f32_32x32x16_bf16 v[80:95], v[220:223], v[10:13], v[80:95]
	v_mfma_f32_32x32x16_bf16 v[64:79], v[224:227], v[10:13], v[64:79]
	v_mfma_f32_32x32x16_bf16 v[48:63], v[228:231], v[10:13], v[48:63]
	v_mfma_f32_32x32x16_bf16 v[32:47], v[232:235], v[10:13], v[32:47]
	s_waitcnt lgkmcnt(14)
	v_mfma_f32_32x32x16_bf16 v[80:95], v[236:239], v[6:9], v[80:95]
	s_waitcnt lgkmcnt(12)
	v_mfma_f32_32x32x16_bf16 v[64:79], v[240:243], v[6:9], v[64:79]
	s_waitcnt lgkmcnt(10)
	v_mfma_f32_32x32x16_bf16 v[48:63], v[104:107], v[6:9], v[48:63]
	s_waitcnt lgkmcnt(8)
	v_mfma_f32_32x32x16_bf16 v[32:47], v[108:111], v[6:9], v[32:47]
	s_waitcnt lgkmcnt(6)
	v_mfma_f32_32x32x16_bf16 v[80:95], v[112:115], v[2:5], v[80:95]
	s_waitcnt lgkmcnt(4)
	v_mfma_f32_32x32x16_bf16 v[64:79], v[116:119], v[2:5], v[64:79]
	s_waitcnt lgkmcnt(2)
	v_mfma_f32_32x32x16_bf16 v[48:63], v[120:123], v[2:5], v[48:63]
	s_waitcnt lgkmcnt(0)
	v_mfma_f32_32x32x16_bf16 v[32:47], v[124:127], v[2:5], v[32:47]
	s_cmp_lg_u32 s73, 0
	s_cbranch_scc1 .Lfa_e_bar
	s_waitcnt vmcnt(6)
	ds_write_b128 v14, v[160:163] offset:37888
	ds_write_b128 v15, v[164:167] offset:55296
	s_waitcnt vmcnt(5)
	ds_write_b128 v202, v[168:171] offset:37888
	s_waitcnt vmcnt(4)
	ds_write_b128 v203, v[172:175] offset:55296
.Lfa_e_bar:
	s_add_u32 s68, s68, s72
	s_addc_u32 s69, s69, 0
	s_add_u32 s70, s70, s72
	s_addc_u32 s71, s71, 0
	s_waitcnt lgkmcnt(0)
	s_barrier
	s_cmp_eq_u32 s73, 0
	s_cbranch_scc1 .Lfa_o_a
	s_waitcnt vmcnt(2)
	ds_write_b128 v197, v[144:147]
	ds_write_b128 v198, v[148:151] offset:17408
	s_waitcnt vmcnt(1)
	ds_write_b128 v197, v[152:155] offset:8704
	s_waitcnt vmcnt(0)
	ds_write_b128 v199, v[156:159] offset:17408
	global_load_dwordx4 v[160:163], v205, s[68:69]
	global_load_dwordx4 v[164:167], v205, s[70:71]
	global_load_dwordx4 v[168:171], v206, s[68:69]
	global_load_dwordx4 v[172:175], v206, s[70:71]
	s_cmp_eq_u32 s74, 0
	s_cbranch_scc1 .Lfa_o_bar
	s_waitcnt lgkmcnt(3)
.Lfa_o_a:
	v_add_u32_e32 v209, 0x10000, v200
	ds_read_b128 v[212:215], v201 offset:37888
	ds_read_b128 v[216:219], v201 offset:46592
	ds_read_b128 v[220:223], v201 offset:37920
	ds_read_b128 v[224:227], v201 offset:46624
	ds_read_b128 v[228:231], v201 offset:37952
	ds_read_b128 v[232:235], v201 offset:46656
	ds_read_b128 v[236:239], v201 offset:37984
	ds_read_b128 v[240:243], v201 offset:46688
	ds_read_b64_tr_b16 v[244:245], v200 offset:55296
	ds_read_b64_tr_b16 v[246:247], v200 offset:57856
	ds_read_b64_tr_b16 v[248:249], v200 offset:55360
	ds_read_b64_tr_b16 v[250:251], v200 offset:57920
	s_waitcnt lgkmcnt(11)
	v_mfma_f32_32x32x16_bf16 v[96:111], v[212:215], v[128:131], v[16:31]
	s_waitcnt lgkmcnt(10)
	v_mfma_f32_32x32x16_bf16 v[112:127], v[216:219], v[128:131], v[16:31]
	s_waitcnt lgkmcnt(9)
	v_mfma_f32_32x32x16_bf16 v[96:111], v[220:223], v[132:135], v[96:111]
	s_waitcnt lgkmcnt(8)
	v_mfma_f32_32x32x16_bf16 v[112:127], v[224:227], v[132:135], v[112:127]
	s_waitcnt lgkmcnt(7)
	v_mfma_f32_32x32x16_bf16 v[96:111], v[228:231], v[136:139], v[96:111]
	s_waitcnt lgkmcnt(6)
	v_mfma_f32_32x32x16_bf16 v[112:127], v[232:235], v[136:139], v[112:127]
	s_waitcnt lgkmcnt(5)
	v_mfma_f32_32x32x16_bf16 v[96:111], v[236:239], v[140:143], v[96:111]
	s_waitcnt lgkmcnt(4)
	v_mfma_f32_32x32x16_bf16 v[112:127], v[240:243], v[140:143], v[112:127]
	ds_read_b64_tr_b16 v[212:213], v200 offset:55424
	ds_read_b64_tr_b16 v[214:215], v200 offset:57984
	ds_read_b64_tr_b16 v[216:217], v200 offset:55488
	ds_read_b64_tr_b16 v[218:219], v200 offset:58048
	ds_read_b64_tr_b16 v[220:221], v200 offset:60416
	ds_read_b64_tr_b16 v[222:223], v200 offset:62976
	ds_read_b64_tr_b16 v[224:225], v200 offset:60480
	ds_read_b64_tr_b16 v[226:227], v200 offset:63040
	ds_read_b64_tr_b16 v[228:229], v200 offset:60544
	ds_read_b64_tr_b16 v[230:231], v200 offset:63104
	s_cmp_lg_u32 s73, 0
	s_cbranch_scc1 .Lfa_o_now1
	global_load_dwordx4 v[160:163], v205, s[68:69]
	global_load_dwordx4 v[164:167], v205, s[70:71]
	global_load_dwordx4 v[168:171], v206, s[68:69]
	global_load_dwordx4 v[172:175], v206, s[70:71]
.Lfa_o_now1:
	s_nop 3
	v_max3_f32 v0, v96, v97, v112
	v_max3_f32 v2, v98, v99, v113
	s_nop 0
	v_max3_f32 v0, v0, v114, v115
	v_max3_f32 v2, v2, v102, v103
	s_nop 0
	v_max3_f32 v0, v0, v100, v101
	v_max3_f32 v2, v2, v118, v119
	s_nop 0
	v_max3_f32 v0, v0, v116, v117
	v_max3_f32 v2, v2, v106, v107
	s_nop 0
	v_max3_f32 v0, v0, v104, v105
	v_max3_f32 v2, v2, v122, v123
	s_nop 0
	v_max3_f32 v0, v0, v120, v121
	v_max3_f32 v2, v2, v110, v111
	s_nop 0
	v_max3_f32 v0, v0, v108, v109
	v_max3_f32 v2, v2, v126, v127
	s_nop 0
	v_max3_f32 v0, v0, v124, v125
	v_max_f32_e32 v2, v2, v2
	v_max_f32_e32 v0, v0, v0
	v_max_f32_e32 v0, v0, v2
	v_mov_b32_e32 v2, v0
	s_nop 1
	v_permlane32_swap_b32_e32 v0, v2
	v_max_f32_e32 v2, v2, v2
	v_max_f32_e32 v0, v0, v0
	v_max_f32_e32 v0, v0, v2
	v_cmp_lt_f32_e32 vcc, s57, v0
	s_cbranch_vccz .Lfa_o_sm
	v_max_f32_e32 v0, v0, v0
	v_max_f32_e32 v0, 0, v0
	v_add_f32_e32 v182, v182, v0
	v_pk_add_f32 v[96:97], v[96:97], v[0:1] op_sel_hi:[1,0] neg_lo:[0,1] neg_hi:[0,1]
	v_pk_add_f32 v[112:113], v[112:113], v[0:1] op_sel_hi:[1,0] neg_lo:[0,1] neg_hi:[0,1]
	v_pk_add_f32 v[98:99], v[98:99], v[0:1] op_sel_hi:[1,0] neg_lo:[0,1] neg_hi:[0,1]
	v_pk_add_f32 v[114:115], v[114:115], v[0:1] op_sel_hi:[1,0] neg_lo:[0,1] neg_hi:[0,1]
	v_pk_add_f32 v[100:101], v[100:101], v[0:1] op_sel_hi:[1,0] neg_lo:[0,1] neg_hi:[0,1]
	v_pk_add_f32 v[116:117], v[116:117], v[0:1] op_sel_hi:[1,0] neg_lo:[0,1] neg_hi:[0,1]
	v_pk_add_f32 v[102:103], v[102:103], v[0:1] op_sel_hi:[1,0] neg_lo:[0,1] neg_hi:[0,1]
	v_pk_add_f32 v[118:119], v[118:119], v[0:1] op_sel_hi:[1,0] neg_lo:[0,1] neg_hi:[0,1]
	v_pk_add_f32 v[104:105], v[104:105], v[0:1] op_sel_hi:[1,0] neg_lo:[0,1] neg_hi:[0,1]
	v_pk_add_f32 v[120:121], v[120:121], v[0:1] op_sel_hi:[1,0] neg_lo:[0,1] neg_hi:[0,1]
	v_pk_add_f32 v[106:107], v[106:107], v[0:1] op_sel_hi:[1,0] neg_lo:[0,1] neg_hi:[0,1]
	v_pk_add_f32 v[122:123], v[122:123], v[0:1] op_sel_hi:[1,0] neg_lo:[0,1] neg_hi:[0,1]
	v_pk_add_f32 v[108:109], v[108:109], v[0:1] op_sel_hi:[1,0] neg_lo:[0,1] neg_hi:[0,1]
	v_pk_add_f32 v[124:125], v[124:125], v[0:1] op_sel_hi:[1,0] neg_lo:[0,1] neg_hi:[0,1]
	v_pk_add_f32 v[110:111], v[110:111], v[0:1] op_sel_hi:[1,0] neg_lo:[0,1] neg_hi:[0,1]
	v_pk_add_f32 v[126:127], v[126:127], v[0:1] op_sel_hi:[1,0] neg_lo:[0,1] neg_hi:[0,1]
	v_exp_f32_e64 v0, -v0
	v_xor_b32_e32 v16, 0x80000000, v182
	v_mov_b32_e32 v17, v16
	v_mov_b32_e32 v18, v16
	v_mov_b32_e32 v19, v16
	v_mov_b32_e32 v20, v16
	v_mov_b32_e32 v21, v16
	v_mov_b32_e32 v22, v16
	v_mov_b32_e32 v23, v16
	v_mov_b32_e32 v24, v16
	v_mov_b32_e32 v25, v16
	v_mov_b32_e32 v26, v16
	v_mov_b32_e32 v27, v16
	v_mov_b32_e32 v28, v16
	v_mov_b32_e32 v29, v16
	v_mov_b32_e32 v30, v16
	v_mov_b32_e32 v31, v16
	v_mul_f32_e32 v183, v183, v0
	v_pk_mul_f32 v[94:95], v[94:95], v[0:1] op_sel_hi:[1,0]
	v_pk_mul_f32 v[92:93], v[92:93], v[0:1] op_sel_hi:[1,0]
	v_pk_mul_f32 v[90:91], v[90:91], v[0:1] op_sel_hi:[1,0]
	v_pk_mul_f32 v[88:89], v[88:89], v[0:1] op_sel_hi:[1,0]
	v_pk_mul_f32 v[86:87], v[86:87], v[0:1] op_sel_hi:[1,0]
	v_pk_mul_f32 v[84:85], v[84:85], v[0:1] op_sel_hi:[1,0]
	v_pk_mul_f32 v[82:83], v[82:83], v[0:1] op_sel_hi:[1,0]
	v_pk_mul_f32 v[80:81], v[80:81], v[0:1] op_sel_hi:[1,0]
	v_pk_mul_f32 v[78:79], v[78:79], v[0:1] op_sel_hi:[1,0]
	v_pk_mul_f32 v[76:77], v[76:77], v[0:1] op_sel_hi:[1,0]
	v_pk_mul_f32 v[74:75], v[74:75], v[0:1] op_sel_hi:[1,0]
	v_pk_mul_f32 v[72:73], v[72:73], v[0:1] op_sel_hi:[1,0]
	v_pk_mul_f32 v[70:71], v[70:71], v[0:1] op_sel_hi:[1,0]
	v_pk_mul_f32 v[68:69], v[68:69], v[0:1] op_sel_hi:[1,0]
	v_pk_mul_f32 v[66:67], v[66:67], v[0:1] op_sel_hi:[1,0]
	v_pk_mul_f32 v[64:65], v[64:65], v[0:1] op_sel_hi:[1,0]
	v_pk_mul_f32 v[62:63], v[62:63], v[0:1] op_sel_hi:[1,0]
	v_pk_mul_f32 v[60:61], v[60:61], v[0:1] op_sel_hi:[1,0]
	v_pk_mul_f32 v[58:59], v[58:59], v[0:1] op_sel_hi:[1,0]
	v_pk_mul_f32 v[56:57], v[56:57], v[0:1] op_sel_hi:[1,0]
	v_pk_mul_f32 v[54:55], v[54:55], v[0:1] op_sel_hi:[1,0]
	v_pk_mul_f32 v[52:53], v[52:53], v[0:1] op_sel_hi:[1,0]
	v_pk_mul_f32 v[50:51], v[50:51], v[0:1] op_sel_hi:[1,0]
	v_pk_mul_f32 v[48:49], v[48:49], v[0:1] op_sel_hi:[1,0]
	v_pk_mul_f32 v[46:47], v[46:47], v[0:1] op_sel_hi:[1,0]
	v_pk_mul_f32 v[44:45], v[44:45], v[0:1] op_sel_hi:[1,0]
	v_pk_mul_f32 v[42:43], v[42:43], v[0:1] op_sel_hi:[1,0]
	v_pk_mul_f32 v[40:41], v[40:41], v[0:1] op_sel_hi:[1,0]
	v_pk_mul_f32 v[38:39], v[38:39], v[0:1] op_sel_hi:[1,0]
	v_pk_mul_f32 v[36:37], v[36:37], v[0:1] op_sel_hi:[1,0]
	v_pk_mul_f32 v[34:35], v[34:35], v[0:1] op_sel_hi:[1,0]
	v_pk_mul_f32 v[32:33], v[32:33], v[0:1] op_sel_hi:[1,0]
.Lfa_o_sm:
	s_waitcnt lgkmcnt(9)
	ds_read_b64_tr_b16 v[232:233], v200 offset:60608
	ds_read_b64_tr_b16 v[234:235], v200 offset:63168
	ds_read_b64_tr_b16 v[236:237], v209 offset:0
	ds_read_b64_tr_b16 v[238:239], v209 offset:2560
	ds_read_b64_tr_b16 v[240:241], v209 offset:64
	ds_read_b64_tr_b16 v[242:243], v209 offset:2624
	v_exp_f32_e32 v176, v96
	v_exp_f32_e32 v177, v112
	v_exp_f32_e32 v0, v97
	v_exp_f32_e32 v2, v113
	v_exp_f32_e32 v204, v114
	v_add_f32_e32 v3, v177, v176
	v_exp_f32_e32 v8, v115
	v_pk_add_f32 v[4:5], v[2:3], v[0:1]
	v_exp_f32_e32 v3, v98
	v_pk_add_f32 v[4:5], v[4:5], v[4:5] op_sel_hi:[0,1]
	v_exp_f32_e32 v4, v99
	v_exp_f32_e32 v112, v117
	v_add_f32_e32 v9, v204, v3
	v_exp_f32_e32 v114, v123
	v_pk_add_f32 v[6:7], v[8:9], v[4:5]
	v_exp_f32_e32 v5, v100
	v_pk_add_f32 v[6:7], v[6:7], v[6:7] op_sel_hi:[0,1]
	v_exp_f32_e32 v9, v116
	v_exp_f32_e32 v6, v101
	v_exp_f32_e32 v100, v119
	v_exp_f32_e32 v116, v125
	v_add_f32_e32 v113, v9, v5
	v_pk_add_f32 v[10:11], v[112:113], v[6:7]
	v_exp_f32_e32 v7, v102
	v_pk_add_f32 v[10:11], v[10:11], v[10:11] op_sel_hi:[0,1]
	v_exp_f32_e32 v113, v118
	v_exp_f32_e32 v10, v103
	v_exp_f32_e32 v102, v121
	v_exp_f32_e32 v118, v127
	v_add_f32_e32 v101, v113, v7
	v_pk_add_f32 v[12:13], v[100:101], v[10:11]
	v_exp_f32_e32 v11, v104
	v_pk_add_f32 v[12:13], v[12:13], v[12:13] op_sel_hi:[0,1]
	v_exp_f32_e32 v101, v120
	v_exp_f32_e32 v12, v105
	v_cvt_pk_bf16_f32 v98, v5, v6
	v_cvt_pk_bf16_f32 v99, v7, v10
	v_add_f32_e32 v103, v101, v11
	v_pk_add_f32 v[96:97], v[102:103], v[12:13]
	v_exp_f32_e32 v13, v106
	v_pk_add_f32 v[104:105], v[96:97], v[96:97] op_sel_hi:[0,1]
	v_exp_f32_e32 v103, v122
	v_exp_f32_e32 v104, v107
	v_cvt_pk_bf16_f32 v6, v177, v2
	v_cvt_pk_bf16_f32 v7, v204, v8
	v_add_f32_e32 v115, v103, v13
	v_pk_add_f32 v[96:97], v[114:115], v[104:105]
	v_exp_f32_e32 v105, v108
	v_pk_add_f32 v[106:107], v[96:97], v[96:97] op_sel_hi:[0,1]
	v_exp_f32_e32 v115, v124
	v_exp_f32_e32 v106, v109
	v_cvt_pk_bf16_f32 v8, v9, v112
	v_cvt_pk_bf16_f32 v9, v113, v100
	v_add_f32_e32 v117, v115, v105
	v_pk_add_f32 v[96:97], v[116:117], v[106:107]
	v_exp_f32_e32 v107, v110
	v_pk_add_f32 v[108:109], v[96:97], v[96:97] op_sel_hi:[0,1]
	v_exp_f32_e32 v110, v126
	v_exp_f32_e32 v108, v111
	v_cvt_pk_bf16_f32 v2, v101, v102
	v_cvt_pk_bf16_f32 v10, v11, v12
	v_add_f32_e32 v119, v110, v107
	v_pk_add_f32 v[96:97], v[118:119], v[108:109]
	v_cvt_pk_bf16_f32 v11, v13, v104
	v_add_f32_e32 v96, v96, v97
	v_cvt_pk_bf16_f32 v97, v3, v4
	v_cvt_pk_bf16_f32 v3, v103, v114
	v_add_f32_e32 v183, v183, v96
	v_cvt_pk_bf16_f32 v96, v176, v0
	v_cvt_pk_bf16_f32 v12, v105, v106
	v_cvt_pk_bf16_f32 v13, v107, v108
	v_cvt_pk_bf16_f32 v4, v115, v116
	v_cvt_pk_bf16_f32 v5, v110, v118
	s_waitcnt lgkmcnt(3)
	ds_read_b64_tr_b16 v[104:105], v209 offset:128
	ds_read_b64_tr_b16 v[106:107], v209 offset:2688
	ds_read_b64_tr_b16 v[108:109], v209 offset:192
	ds_read_b64_tr_b16 v[110:111], v209 offset:2752
	ds_read_b64_tr_b16 v[112:113], v209 offset:5120
	ds_read_b64_tr_b16 v[114:115], v209 offset:7680
	ds_read_b64_tr_b16 v[116:117], v209 offset:5184
	ds_read_b64_tr_b16 v[118:119], v209 offset:7744
	ds_read_b64_tr_b16 v[120:121], v209 offset:5248
	ds_read_b64_tr_b16 v[122:123], v209 offset:7808
	ds_read_b64_tr_b16 v[124:125], v209 offset:5312
	ds_read_b64_tr_b16 v[126:127], v209 offset:7872
	v_mfma_f32_32x32x16_bf16 v[80:95], v[244:247], v[96:99], v[80:95]
	v_mfma_f32_32x32x16_bf16 v[64:79], v[248:251], v[96:99], v[64:79]
	v_mfma_f32_32x32x16_bf16 v[48:63], v[212:215], v[96:99], v[48:63]
	v_mfma_f32_32x32x16_bf16 v[32:47], v[216:219], v[96:99], v[32:47]
	v_mfma_f32_32x32x16_bf16 v[80:95], v[220:223], v[10:13], v[80:95]
	v_mfma_f32_32x32x16_bf16 v[64:79], v[224:227], v[10:13], v[64:79]
	v_mfma_f32_32x32x16_bf16 v[48:63], v[228:231], v[10:13], v[48:63]
	v_mfma_f32_32x32x16_bf16 v[32:47], v[232:235], v[10:13], v[32:47]
	s_waitcnt lgkmcnt(14)
	v_mfma_f32_32x32x16_bf16 v[80:95], v[236:239], v[6:9], v[80:95]
	s_waitcnt lgkmcnt(12)
	v_mfma_f32_32x32x16_bf16 v[64:79], v[240:243], v[6:9], v[64:79]
	s_waitcnt lgkmcnt(10)
	v_mfma_f32_32x32x16_bf16 v[48:63], v[104:107], v[6:9], v[48:63]
	s_waitcnt lgkmcnt(8)
	v_mfma_f32_32x32x16_bf16 v[32:47], v[108:111], v[6:9], v[32:47]
	s_waitcnt lgkmcnt(6)
	v_mfma_f32_32x32x16_bf16 v[80:95], v[112:115], v[2:5], v[80:95]
	s_waitcnt lgkmcnt(4)
	v_mfma_f32_32x32x16_bf16 v[64:79], v[116:119], v[2:5], v[64:79]
	s_waitcnt lgkmcnt(2)
	v_mfma_f32_32x32x16_bf16 v[48:63], v[120:123], v[2:5], v[48:63]
	s_waitcnt lgkmcnt(0)
	v_mfma_f32_32x32x16_bf16 v[32:47], v[124:127], v[2:5], v[32:47]
	s_cmp_lg_u32 s73, 0
	s_cbranch_scc1 .Lfa_o_bar
	s_waitcnt vmcnt(6)
	ds_write_b128 v197, v[144:147]
	ds_write_b128 v198, v[148:151] offset:17408
	s_waitcnt vmcnt(5)
	ds_write_b128 v197, v[152:155] offset:8704
	s_waitcnt vmcnt(4)
	ds_write_b128 v199, v[156:159] offset:17408
.Lfa_o_bar:
	s_add_u32 s68, s68, s72
	s_addc_u32 s69, s69, 0
	s_add_u32 s70, s70, s72
	s_addc_u32 s71, s71, 0
	s_waitcnt lgkmcnt(0)
	s_barrier
	s_add_i32 s1, s1, 2
	s_addk_i32 s30, 0x80
	s_add_i32 s75, s1, 3
	s_cmp_lt_i32 s75, s62
	s_cbranch_scc1 .Lfa_loop
	s_branch .LBB0_709
